# scan tasks: groups sharing 128B lines of Z/YP mapped to one XCD; side-work rows grouped per XCD (L2 reuse of neighbour rows)
# speedup vs baseline: 1.0409x; 1.0257x over previous
.LBB0_247:
	s_bfe_u32 s1, s38, 0x60001
	s_and_b32 s0, s1, 0x30
	s_bfe_u32 s10, s1, 0x20002
	s_or_b32 s0, s0, s10
	s_and_b32 s10, s1, 3
	s_lshl_b32 s10, s10, 2
	s_or_b32 s1, s0, s10
	s_or_b32 s18, s1, s64
	v_lshl_or_b32 v0, s18, 6, v12
	v_lshlrev_b32_e32 v1, 4, v0
	global_load_dwordx4 v[18:21], v1, s[72:73]
	global_load_dwordx4 v[22:25], v1, s[72:73] offset:256
	global_load_dwordx4 v[26:29], v1, s[72:73] offset:512
	global_load_dwordx4 v[30:33], v1, s[72:73] offset:768
	s_load_dwordx4 s[44:47], s[58:59], 0x60
	s_load_dwordx4 s[8:11], s[58:59], 0x70
	v_lshlrev_b32_e32 v2, 6, v0
	v_lshl_add_u32 v2, v13, 4, v2
	v_lshl_or_b32 v3, s18, 4, v12
	v_lshlrev_b32_e32 v3, 8, v3
	v_lshl_add_u32 v3, v13, 4, v3
	s_waitcnt lgkmcnt(0)
	global_load_dwordx4 v[50:53], v2, s[44:45]
	global_load_dwordx4 v[54:57], v2, s[44:45] offset:1024
	global_load_dwordx4 v[58:61], v2, s[44:45] offset:2048
	global_load_dwordx4 v[62:65], v2, s[44:45] offset:3072
	global_load_dwordx4 v[66:69], v2, s[46:47]
	global_load_dwordx4 v[70:73], v2, s[46:47] offset:1024
	global_load_dwordx4 v[74:77], v2, s[46:47] offset:2048
	global_load_dwordx4 v[78:81], v2, s[46:47] offset:3072
	global_load_dwordx4 v[34:37], v3, s[8:9]
	global_load_dwordx4 v[38:41], v3, s[8:9] offset:64
	global_load_dwordx4 v[42:45], v3, s[8:9] offset:128
	global_load_dwordx4 v[46:49], v3, s[8:9] offset:192
	global_load_dwordx4 v[188:191], v3, s[10:11]
	global_load_dwordx4 v[192:195], v3, s[10:11] offset:64
	global_load_dwordx4 v[196:199], v3, s[10:11] offset:128
	global_load_dwordx4 v[200:203], v3, s[10:11] offset:192
	s_and_b64 s[82:83], s[84:85], exec
	s_cselect_b32 s13, 10, 8
	s_cselect_b32 s0, 0x1000, 0
	s_lshl_b32 s12, 1, s13
	s_lshl_b32 s10, s3, s13
	s_add_i32 s10, s10, s0
	s_lshl_b32 s20, s25, 8
	s_sub_i32 s0, s12, 1
	s_sub_i32 s0, s0, s20
	s_mov_b32 s86, 0x8000
	s_mov_b32 s87, 0
	s_mov_b32 s88, 0x4000
	s_mov_b32 s89, 0
	s_mov_b32 s15, 1
	s_cmp_eq_u32 s39, 0
	s_cselect_b32 s0, s20, s0
	s_cbranch_scc1 .Lsc_fwd
	s_mov_b32 s86, 0xffff8000
	s_mov_b32 s87, -1
	s_mov_b32 s88, 0xffffc000
	s_mov_b32 s89, -1
	s_mov_b32 s15, -1

.LBB0_346:
	s_and_b32 s0, s6, 7
	s_lshr_b32 s1, s4, 3
	s_mul_i32 s0, s0, s1
	s_lshr_b32 s1, s6, 3
	s_add_i32 s6, s0, s1
	s_cmpk_gt_i32 s14, 0xa8
	s_cselect_b64 s[10:11], -1, 0
	s_andn2_b64 vcc, exec, s[62:63]
	s_movk_i32 s8, 0x2400
	s_cbranch_vccnz .LBB0_351
	s_add_i32 s3, s36, 0xfffffd00
	s_and_b64 s[0:1], s[10:11], exec
	s_cselect_b32 s3, s3, s36
	s_add_i32 s5, s36, 0xfffffb00
	s_and_b64 s[0:1], s[10:11], exec
	s_cselect_b32 s0, s5, s36
	s_add_i32 s12, s0, s3
	s_mul_hi_i32 s69, s0, 0x3000
	s_mul_i32 s68, s0, 0x3000
	s_ashr_i32 s13, s12, 31
	s_or_b64 s[0:1], s[68:69], s[12:13]
	s_mov_b32 s0, s21
	s_cmp_lg_u64 s[0:1], 0
	s_cbranch_scc0 .LBB0_580
	s_ashr_i32 s8, s13, 31
	s_add_u32 s0, s12, s8
	s_mov_b32 s9, s8
	s_addc_u32 s1, s13, s8
	s_xor_b64 s[70:71], s[0:1], s[8:9]
	v_cvt_f32_u32_e32 v0, s70
	v_cvt_f32_u32_e32 v1, s71
	s_sub_u32 s3, 0, s70
	s_subb_u32 s5, 0, s71
	v_fmac_f32_e32 v0, 0x4f800000, v1
	v_rcp_f32_e32 v0, v0
	s_nop 0
	v_mul_f32_e32 v0, 0x5f7ffffc, v0
	v_mul_f32_e32 v1, 0x2f800000, v0
	v_trunc_f32_e32 v1, v1
	v_fmac_f32_e32 v0, 0xcf800000, v1
	v_cvt_u32_f32_e32 v1, v1
	v_cvt_u32_f32_e32 v0, v0
	v_readfirstlane_b32 s7, v1
	v_readfirstlane_b32 s0, v0
	s_mul_i32 s1, s3, s7
	s_mul_hi_u32 s15, s3, s0
	s_mul_i32 s13, s5, s0
	s_add_i32 s1, s15, s1
	s_add_i32 s1, s1, s13
	s_mul_i32 s18, s3, s0
	s_mul_i32 s15, s0, s1
	s_mul_hi_u32 s19, s0, s18
	s_mul_hi_u32 s13, s0, s1
	s_add_u32 s15, s19, s15
	s_addc_u32 s13, 0, s13
	s_mul_hi_u32 s20, s7, s18
	s_mul_i32 s18, s7, s18
	s_add_u32 s15, s15, s18
	s_mul_hi_u32 s19, s7, s1
	s_addc_u32 s13, s13, s20
	s_addc_u32 s15, s19, 0
	s_mul_i32 s1, s7, s1
	s_add_u32 s1, s13, s1
	s_addc_u32 s13, 0, s15
	s_add_u32 s15, s0, s1
	s_cselect_b64 s[0:1], -1, 0
	s_cmp_lg_u64 s[0:1], 0
	s_addc_u32 s7, s7, s13
	s_mul_i32 s0, s3, s7
	s_mul_hi_u32 s1, s3, s15
	s_add_i32 s0, s1, s0
	s_mul_i32 s5, s5, s15
	s_add_i32 s0, s0, s5
	s_mul_i32 s3, s3, s15
	s_mul_hi_u32 s5, s7, s3
	s_mul_i32 s13, s7, s3
	s_mul_i32 s19, s15, s0
	s_mul_hi_u32 s3, s15, s3
	s_mul_hi_u32 s18, s15, s0
	s_add_u32 s3, s3, s19
	s_addc_u32 s18, 0, s18
	s_add_u32 s3, s3, s13
	s_mul_hi_u32 s1, s7, s0
	s_addc_u32 s3, s18, s5
	s_addc_u32 s1, s1, 0
	s_mul_i32 s0, s7, s0
	s_add_u32 s0, s3, s0
	s_addc_u32 s3, 0, s1
	s_add_u32 s5, s15, s0
	s_cselect_b64 s[0:1], -1, 0
	s_cmp_lg_u64 s[0:1], 0
	s_addc_u32 s3, s7, s3
	s_ashr_i32 s0, s69, 31
	s_add_u32 s18, s68, s0
	s_mov_b32 s1, s0
	s_addc_u32 s19, s69, s0
	s_xor_b64 s[18:19], s[18:19], s[0:1]
	s_mul_i32 s13, s18, s3
	s_mul_hi_u32 s15, s18, s5
	s_mul_hi_u32 s7, s18, s3
	s_add_u32 s13, s15, s13
	s_addc_u32 s7, 0, s7
	s_mul_hi_u32 s20, s19, s5
	s_mul_i32 s5, s19, s5
	s_add_u32 s5, s13, s5
	s_mul_hi_u32 s15, s19, s3
	s_addc_u32 s5, s7, s20
	s_addc_u32 s7, s15, 0
	s_mul_i32 s3, s19, s3
	s_add_u32 s3, s5, s3
	s_addc_u32 s5, 0, s7
	s_mul_i32 s7, s70, s5
	s_mul_hi_u32 s13, s70, s3
	s_add_i32 s7, s13, s7
	s_mul_i32 s13, s71, s3
	s_add_i32 s7, s7, s13
	s_sub_i32 s13, s19, s7
	s_mul_i32 s15, s70, s3
	s_sub_u32 s15, s18, s15
	s_cselect_b64 s[36:37], -1, 0
	s_cmp_lg_u64 s[36:37], 0
	s_subb_u32 s13, s13, s71
	s_sub_u32 s18, s15, s70
	s_cselect_b64 s[38:39], -1, 0
	s_cmp_lg_u64 s[38:39], 0
	s_subb_u32 s13, s13, 0
	s_cmp_ge_u32 s13, s71
	s_cselect_b32 s20, -1, 0
	s_cmp_ge_u32 s18, s70
	s_cselect_b32 s18, -1, 0
	s_cmp_eq_u32 s13, s71
	s_cselect_b32 s13, s18, s20
	s_add_u32 s18, s3, 1
	s_addc_u32 s20, s5, 0
	s_add_u32 s25, s3, 2
	s_addc_u32 s38, s5, 0
	s_cmp_lg_u32 s13, 0
	s_cselect_b32 s13, s25, s18
	s_cselect_b32 s18, s38, s20
	s_cmp_lg_u64 s[36:37], 0
	s_subb_u32 s7, s19, s7
	s_cmp_ge_u32 s7, s71
	s_cselect_b32 s19, -1, 0
	s_cmp_ge_u32 s15, s70
	s_cselect_b32 s15, -1, 0
	s_cmp_eq_u32 s7, s71
	s_cselect_b32 s7, s15, s19
	s_cmp_lg_u32 s7, 0
	s_cselect_b32 s19, s18, s5
	s_cselect_b32 s18, s13, s3
	s_xor_b64 s[0:1], s[0:1], s[8:9]
	s_xor_b64 s[8:9], s[18:19], s[0:1]
	s_sub_u32 s8, s8, s0
	s_cbranch_execnz .LBB0_350
